# GEMM tile loop: first K iteration peeled with C=0 first-touch MFMAs; accumulator clears removed
# speedup vs baseline: 1.0102x; 1.0017x over previous
.LBB0_65:
	s_add_u32 s0, s12, 0x80
	s_addc_u32 s1, s13, 0
	s_add_u32 s12, s10, 0x100
	s_addc_u32 s13, s11, 0
	s_mov_b32 s10, 0
	v_add_u32_e32 v0, s61, v242
	s_waitcnt lgkmcnt(0)
	ds_read_b128 v[130:133], v0
	ds_read_b128 v[134:137], v0 offset:1024
	ds_read_b128 v[138:141], v0 offset:2048
	ds_read_b128 v[142:145], v0 offset:3072
	v_add_u32_e32 v0, s20, v242
	ds_read_b128 v[146:149], v0
	ds_read_b128 v[150:153], v0 offset:1024
	ds_read_b128 v[154:157], v0 offset:2048
	ds_read_b128 v[158:161], v0 offset:3072
	s_add_i32 s14, s10, 2
	s_add_u32 s15, s0, 0x80
	s_addc_u32 s11, s1, 0
	s_cmp_eq_u32 s27, s10
	s_cselect_b32 s10, s22, s15
	s_cselect_b32 s11, s23, s11
	s_cselect_b32 s53, s25, s13
	s_cselect_b32 s52, s24, s12
	v_lshl_add_u64 v[216:217], s[0:1], 0, v[194:195]
	s_add_i32 m0, s5, 0xc000
	ds_read_b128 v[162:165], v246
	ds_read_b128 v[166:169], v246 offset:1024
	ds_read_b128 v[170:173], v246 offset:2048
	ds_read_b128 v[174:177], v246 offset:3072
	ds_read_b128 v[200:203], v246 offset:4096
	ds_read_b128 v[204:207], v246 offset:5120
	ds_read_b128 v[208:211], v246 offset:6144
	ds_read_b128 v[212:215], v246 offset:7168
	global_load_lds_dwordx4 v[216:217], off
	v_lshl_add_u64 v[216:217], s[0:1], 0, v[196:197]
	s_add_i32 m0, s5, 0xe000
	s_nop 0
	global_load_lds_dwordx4 v[216:217], off
	s_waitcnt vmcnt(8)
	s_waitcnt lgkmcnt(0)
	s_barrier
	v_mfma_f32_16x16x32_bf16 v[30:33], v[130:133], v[162:165], 0
	v_mfma_f32_16x16x32_bf16 v[26:29], v[138:141], v[162:165], 0
	v_mfma_f32_16x16x32_bf16 v[18:21], v[130:133], v[170:173], 0
	v_mfma_f32_16x16x32_bf16 v[10:13], v[138:141], v[170:173], 0
	v_mfma_f32_16x16x32_bf16 v[126:129], v[130:133], v[200:203], 0
	v_mfma_f32_16x16x32_bf16 v[122:125], v[138:141], v[200:203], 0
	v_mfma_f32_16x16x32_bf16 v[110:113], v[130:133], v[208:211], 0
	v_mfma_f32_16x16x32_bf16 v[106:109], v[138:141], v[208:211], 0
	v_mfma_f32_16x16x32_bf16 v[30:33], v[134:137], v[166:169], v[30:33]
	v_mfma_f32_16x16x32_bf16 v[26:29], v[142:145], v[166:169], v[26:29]
	v_mfma_f32_16x16x32_bf16 v[18:21], v[134:137], v[174:177], v[18:21]
	v_mfma_f32_16x16x32_bf16 v[10:13], v[142:145], v[174:177], v[10:13]
	v_mfma_f32_16x16x32_bf16 v[126:129], v[134:137], v[204:207], v[126:129]
	v_mfma_f32_16x16x32_bf16 v[122:125], v[142:145], v[204:207], v[122:125]
	v_mfma_f32_16x16x32_bf16 v[110:113], v[134:137], v[212:215], v[110:113]
	v_mfma_f32_16x16x32_bf16 v[106:109], v[142:145], v[212:215], v[106:109]
	v_mfma_f32_16x16x32_bf16 v[22:25], v[146:149], v[162:165], 0
	v_mfma_f32_16x16x32_bf16 v[14:17], v[154:157], v[162:165], 0
	v_mfma_f32_16x16x32_bf16 v[6:9], v[146:149], v[170:173], 0
	v_mfma_f32_16x16x32_bf16 v[2:5], v[154:157], v[170:173], 0
	v_mfma_f32_16x16x32_bf16 v[118:121], v[146:149], v[200:203], 0
	v_mfma_f32_16x16x32_bf16 v[114:117], v[154:157], v[200:203], 0
	v_mfma_f32_16x16x32_bf16 v[102:105], v[146:149], v[208:211], 0
	v_mfma_f32_16x16x32_bf16 v[98:101], v[154:157], v[208:211], 0
	v_mfma_f32_16x16x32_bf16 v[22:25], v[150:153], v[166:169], v[22:25]
	v_mfma_f32_16x16x32_bf16 v[14:17], v[158:161], v[166:169], v[14:17]
	v_mfma_f32_16x16x32_bf16 v[6:9], v[150:153], v[174:177], v[6:9]
	v_mfma_f32_16x16x32_bf16 v[2:5], v[158:161], v[174:177], v[2:5]
	v_mfma_f32_16x16x32_bf16 v[118:121], v[150:153], v[204:207], v[118:121]
	v_mfma_f32_16x16x32_bf16 v[114:117], v[158:161], v[204:207], v[114:117]
	v_mfma_f32_16x16x32_bf16 v[102:105], v[150:153], v[212:215], v[102:105]
	v_mfma_f32_16x16x32_bf16 v[98:101], v[158:161], v[212:215], v[98:101]
	s_barrier
	s_mov_b32 m0, s62
	v_lshl_add_u64 v[216:217], s[52:53], 0, v[178:179]
	v_lshl_add_u64 v[218:219], s[52:53], 0, v[180:181]
	s_add_u32 s52, s52, s96
	ds_read_b128 v[162:165], v246 offset:16384
	ds_read_b128 v[166:169], v246 offset:17408
	ds_read_b128 v[170:173], v246 offset:18432
	ds_read_b128 v[174:177], v246 offset:19456
	ds_read_b128 v[200:203], v246 offset:20480
	ds_read_b128 v[204:207], v246 offset:21504
	ds_read_b128 v[208:211], v246 offset:22528
	ds_read_b128 v[212:215], v246 offset:23552
	global_load_lds_dwordx4 v[216:217], off
	s_mov_b32 m0, s63
	s_addc_u32 s53, s53, 0
	global_load_lds_dwordx4 v[218:219], off
	v_lshl_add_u64 v[220:221], s[52:53], 0, v[178:179]
	s_mov_b32 m0, s21
	v_lshl_add_u64 v[222:223], s[52:53], 0, v[180:181]
	global_load_lds_dwordx4 v[220:221], off
	s_mov_b32 m0, s4
	v_lshl_add_u64 v[224:225], s[10:11], 0, v[178:179]
	global_load_lds_dwordx4 v[222:223], off
	s_mov_b32 m0, s5
	v_lshl_add_u64 v[226:227], s[10:11], 0, v[180:181]
	global_load_lds_dwordx4 v[224:225], off
	s_mov_b32 m0, s60
	s_nop 0
	global_load_lds_dwordx4 v[226:227], off
	s_waitcnt vmcnt(8)
	s_waitcnt lgkmcnt(0)
	s_barrier
	v_mfma_f32_16x16x32_bf16 v[94:97], v[130:133], v[162:165], 0
	v_mfma_f32_16x16x32_bf16 v[90:93], v[138:141], v[162:165], 0
	v_mfma_f32_16x16x32_bf16 v[78:81], v[130:133], v[170:173], 0
	v_mfma_f32_16x16x32_bf16 v[74:77], v[138:141], v[170:173], 0
	v_mfma_f32_16x16x32_bf16 v[62:65], v[130:133], v[200:203], 0
	v_mfma_f32_16x16x32_bf16 v[58:61], v[138:141], v[200:203], 0
	v_mfma_f32_16x16x32_bf16 v[46:49], v[130:133], v[208:211], 0
	v_mfma_f32_16x16x32_bf16 v[42:45], v[138:141], v[208:211], 0
	v_mfma_f32_16x16x32_bf16 v[94:97], v[134:137], v[166:169], v[94:97]
	v_mfma_f32_16x16x32_bf16 v[90:93], v[142:145], v[166:169], v[90:93]
	v_mfma_f32_16x16x32_bf16 v[78:81], v[134:137], v[174:177], v[78:81]
	v_mfma_f32_16x16x32_bf16 v[74:77], v[142:145], v[174:177], v[74:77]
	v_mfma_f32_16x16x32_bf16 v[62:65], v[134:137], v[204:207], v[62:65]
	v_mfma_f32_16x16x32_bf16 v[58:61], v[142:145], v[204:207], v[58:61]
	v_mfma_f32_16x16x32_bf16 v[46:49], v[134:137], v[212:215], v[46:49]
	v_mfma_f32_16x16x32_bf16 v[42:45], v[142:145], v[212:215], v[42:45]
	v_mfma_f32_16x16x32_bf16 v[86:89], v[146:149], v[162:165], 0
	v_mfma_f32_16x16x32_bf16 v[82:85], v[154:157], v[162:165], 0
	v_mfma_f32_16x16x32_bf16 v[70:73], v[146:149], v[170:173], 0
	v_mfma_f32_16x16x32_bf16 v[66:69], v[154:157], v[170:173], 0
	v_mfma_f32_16x16x32_bf16 v[54:57], v[146:149], v[200:203], 0
	v_mfma_f32_16x16x32_bf16 v[50:53], v[154:157], v[200:203], 0
	v_mfma_f32_16x16x32_bf16 v[38:41], v[146:149], v[208:211], 0
	v_mfma_f32_16x16x32_bf16 v[34:37], v[154:157], v[208:211], 0
	v_mfma_f32_16x16x32_bf16 v[86:89], v[150:153], v[166:169], v[86:89]
	v_mfma_f32_16x16x32_bf16 v[82:85], v[158:161], v[166:169], v[82:85]
	v_mfma_f32_16x16x32_bf16 v[70:73], v[150:153], v[174:177], v[70:73]
	v_mfma_f32_16x16x32_bf16 v[66:69], v[158:161], v[174:177], v[66:69]
	v_mfma_f32_16x16x32_bf16 v[54:57], v[150:153], v[204:207], v[54:57]
	v_mfma_f32_16x16x32_bf16 v[50:53], v[158:161], v[204:207], v[50:53]
	v_mfma_f32_16x16x32_bf16 v[38:41], v[150:153], v[212:215], v[38:41]
	v_mfma_f32_16x16x32_bf16 v[34:37], v[158:161], v[212:215], v[34:37]
	s_barrier
	v_add_u32_e32 v0, s6, v242
	ds_read_b128 v[130:133], v0
	ds_read_b128 v[134:137], v0 offset:1024
	ds_read_b128 v[138:141], v0 offset:2048
	ds_read_b128 v[142:145], v0 offset:3072
	v_add_u32_e32 v0, s94, v242
	ds_read_b128 v[146:149], v0
	ds_read_b128 v[150:153], v0 offset:1024
	ds_read_b128 v[154:157], v0 offset:2048
	ds_read_b128 v[158:161], v0 offset:3072
	s_add_u32 s10, s10, s96
	s_addc_u32 s11, s11, 0
	s_mov_b32 m0, s84
	v_lshl_add_u64 v[228:229], s[10:11], 0, v[178:179]
	ds_read_b128 v[162:165], v246 offset:32768
	ds_read_b128 v[166:169], v246 offset:33792
	ds_read_b128 v[170:173], v246 offset:34816
	ds_read_b128 v[174:177], v246 offset:35840
	ds_read_b128 v[200:203], v246 offset:36864
	ds_read_b128 v[204:207], v246 offset:37888
	ds_read_b128 v[208:211], v246 offset:38912
	ds_read_b128 v[212:215], v246 offset:39936
	global_load_lds_dwordx4 v[228:229], off
	v_lshl_add_u64 v[228:229], s[10:11], 0, v[180:181]
	s_mov_b32 m0, s26
	s_nop 0
	global_load_lds_dwordx4 v[228:229], off
	s_waitcnt vmcnt(8)
	s_waitcnt lgkmcnt(0)
	s_barrier
	v_mfma_f32_16x16x32_bf16 v[30:33], v[130:133], v[162:165], v[30:33]
	v_mfma_f32_16x16x32_bf16 v[26:29], v[138:141], v[162:165], v[26:29]
	v_mfma_f32_16x16x32_bf16 v[18:21], v[130:133], v[170:173], v[18:21]
	v_mfma_f32_16x16x32_bf16 v[10:13], v[138:141], v[170:173], v[10:13]
	v_mfma_f32_16x16x32_bf16 v[126:129], v[130:133], v[200:203], v[126:129]
	v_mfma_f32_16x16x32_bf16 v[122:125], v[138:141], v[200:203], v[122:125]
	v_mfma_f32_16x16x32_bf16 v[110:113], v[130:133], v[208:211], v[110:113]
	v_mfma_f32_16x16x32_bf16 v[106:109], v[138:141], v[208:211], v[106:109]
	v_mfma_f32_16x16x32_bf16 v[30:33], v[134:137], v[166:169], v[30:33]
	v_mfma_f32_16x16x32_bf16 v[26:29], v[142:145], v[166:169], v[26:29]
	v_mfma_f32_16x16x32_bf16 v[18:21], v[134:137], v[174:177], v[18:21]
	v_mfma_f32_16x16x32_bf16 v[10:13], v[142:145], v[174:177], v[10:13]
	v_mfma_f32_16x16x32_bf16 v[126:129], v[134:137], v[204:207], v[126:129]
	v_mfma_f32_16x16x32_bf16 v[122:125], v[142:145], v[204:207], v[122:125]
	v_mfma_f32_16x16x32_bf16 v[110:113], v[134:137], v[212:215], v[110:113]
	v_mfma_f32_16x16x32_bf16 v[106:109], v[142:145], v[212:215], v[106:109]
	v_mfma_f32_16x16x32_bf16 v[22:25], v[146:149], v[162:165], v[22:25]
	v_mfma_f32_16x16x32_bf16 v[14:17], v[154:157], v[162:165], v[14:17]
	v_mfma_f32_16x16x32_bf16 v[6:9], v[146:149], v[170:173], v[6:9]
	v_mfma_f32_16x16x32_bf16 v[2:5], v[154:157], v[170:173], v[2:5]
	v_mfma_f32_16x16x32_bf16 v[118:121], v[146:149], v[200:203], v[118:121]
	v_mfma_f32_16x16x32_bf16 v[114:117], v[154:157], v[200:203], v[114:117]
	v_mfma_f32_16x16x32_bf16 v[102:105], v[146:149], v[208:211], v[102:105]
	v_mfma_f32_16x16x32_bf16 v[98:101], v[154:157], v[208:211], v[98:101]
	v_mfma_f32_16x16x32_bf16 v[22:25], v[150:153], v[166:169], v[22:25]
	v_mfma_f32_16x16x32_bf16 v[14:17], v[158:161], v[166:169], v[14:17]
	v_mfma_f32_16x16x32_bf16 v[6:9], v[150:153], v[174:177], v[6:9]
	v_mfma_f32_16x16x32_bf16 v[2:5], v[158:161], v[174:177], v[2:5]
	v_mfma_f32_16x16x32_bf16 v[118:121], v[150:153], v[204:207], v[118:121]
	v_mfma_f32_16x16x32_bf16 v[114:117], v[158:161], v[204:207], v[114:117]
	v_mfma_f32_16x16x32_bf16 v[102:105], v[150:153], v[212:215], v[102:105]
	v_mfma_f32_16x16x32_bf16 v[98:101], v[158:161], v[212:215], v[98:101]
	s_barrier
	s_mov_b32 m0, s7
	v_lshl_add_u64 v[216:217], v[216:217], 0, s[58:59]
	ds_read_b128 v[162:165], v246 offset:49152
	ds_read_b128 v[166:169], v246 offset:50176
	ds_read_b128 v[170:173], v246 offset:51200
	ds_read_b128 v[174:177], v246 offset:52224
	ds_read_b128 v[200:203], v246 offset:53248
	ds_read_b128 v[204:207], v246 offset:54272
	ds_read_b128 v[208:211], v246 offset:55296
	ds_read_b128 v[212:215], v246 offset:56320
	global_load_lds_dwordx4 v[216:217], off
	v_lshl_add_u64 v[216:217], v[218:219], 0, s[58:59]
	s_mov_b32 m0, s86
	s_nop 0
	global_load_lds_dwordx4 v[216:217], off
	v_lshl_add_u64 v[216:217], v[220:221], 0, s[58:59]
	s_mov_b32 m0, s95
	s_nop 0
	global_load_lds_dwordx4 v[216:217], off
	v_lshl_add_u64 v[216:217], v[222:223], 0, s[58:59]
	s_mov_b32 m0, s74
	s_nop 0
	global_load_lds_dwordx4 v[216:217], off
	v_lshl_add_u64 v[216:217], v[224:225], 0, s[58:59]
	s_mov_b32 m0, s87
	s_nop 0
	global_load_lds_dwordx4 v[216:217], off
	v_lshl_add_u64 v[216:217], v[226:227], 0, s[58:59]
	s_mov_b32 m0, s75
	s_nop 0
	global_load_lds_dwordx4 v[216:217], off
	s_waitcnt vmcnt(8)
	s_waitcnt lgkmcnt(0)
	s_barrier
	v_mfma_f32_16x16x32_bf16 v[94:97], v[130:133], v[162:165], v[94:97]
	v_mfma_f32_16x16x32_bf16 v[90:93], v[138:141], v[162:165], v[90:93]
	v_mfma_f32_16x16x32_bf16 v[78:81], v[130:133], v[170:173], v[78:81]
	v_mfma_f32_16x16x32_bf16 v[74:77], v[138:141], v[170:173], v[74:77]
	v_mfma_f32_16x16x32_bf16 v[62:65], v[130:133], v[200:203], v[62:65]
	v_mfma_f32_16x16x32_bf16 v[58:61], v[138:141], v[200:203], v[58:61]
	v_mfma_f32_16x16x32_bf16 v[46:49], v[130:133], v[208:211], v[46:49]
	v_mfma_f32_16x16x32_bf16 v[42:45], v[138:141], v[208:211], v[42:45]
	v_mfma_f32_16x16x32_bf16 v[94:97], v[134:137], v[166:169], v[94:97]
	v_mfma_f32_16x16x32_bf16 v[90:93], v[142:145], v[166:169], v[90:93]
	v_mfma_f32_16x16x32_bf16 v[78:81], v[134:137], v[174:177], v[78:81]
	v_mfma_f32_16x16x32_bf16 v[74:77], v[142:145], v[174:177], v[74:77]
	v_mfma_f32_16x16x32_bf16 v[62:65], v[134:137], v[204:207], v[62:65]
	v_mfma_f32_16x16x32_bf16 v[58:61], v[142:145], v[204:207], v[58:61]
	v_mfma_f32_16x16x32_bf16 v[46:49], v[134:137], v[212:215], v[46:49]
	v_mfma_f32_16x16x32_bf16 v[42:45], v[142:145], v[212:215], v[42:45]
	v_mfma_f32_16x16x32_bf16 v[86:89], v[146:149], v[162:165], v[86:89]
	v_mfma_f32_16x16x32_bf16 v[82:85], v[154:157], v[162:165], v[82:85]
	v_mfma_f32_16x16x32_bf16 v[70:73], v[146:149], v[170:173], v[70:73]
	v_mfma_f32_16x16x32_bf16 v[66:69], v[154:157], v[170:173], v[66:69]
	v_mfma_f32_16x16x32_bf16 v[54:57], v[146:149], v[200:203], v[54:57]
	v_mfma_f32_16x16x32_bf16 v[50:53], v[154:157], v[200:203], v[50:53]
	v_mfma_f32_16x16x32_bf16 v[38:41], v[146:149], v[208:211], v[38:41]
	v_mfma_f32_16x16x32_bf16 v[34:37], v[154:157], v[208:211], v[34:37]
	v_mfma_f32_16x16x32_bf16 v[86:89], v[150:153], v[166:169], v[86:89]
	v_mfma_f32_16x16x32_bf16 v[82:85], v[158:161], v[166:169], v[82:85]
	v_mfma_f32_16x16x32_bf16 v[70:73], v[150:153], v[174:177], v[70:73]
	v_mfma_f32_16x16x32_bf16 v[66:69], v[158:161], v[174:177], v[66:69]
	v_mfma_f32_16x16x32_bf16 v[54:57], v[150:153], v[204:207], v[54:57]
	v_mfma_f32_16x16x32_bf16 v[50:53], v[158:161], v[204:207], v[50:53]
	v_mfma_f32_16x16x32_bf16 v[38:41], v[150:153], v[212:215], v[38:41]
	v_mfma_f32_16x16x32_bf16 v[34:37], v[158:161], v[212:215], v[34:37]
	s_barrier
	s_add_u32 s0, s0, 0x100
	s_addc_u32 s1, s1, 0
	s_add_u32 s12, s12, 0x100
	s_addc_u32 s13, s13, 0
	s_cmp_ge_u32 s14, s33
	s_mov_b32 s10, s14
	s_cbranch_scc1 .Lml_exit

.Lml_exit:
	v_readlane_b32 s0, v254, 13
	v_readlane_b32 s1, v254, 14
	s_and_b64 vcc, exec, s[0:1]
	s_cbranch_vccz .LBB0_69
	s_barrier
